# attention tile loops: 4 redundant NaN-canonicalising v_max per tile removed from the row-max (VALU-issue-bound loop)
# baseline (speedup 1.0000x reference)
.LBB0_1360:
	v_max_f32_e32 v60, v96, v97
	v_max3_f32 v61, v98, v99, v81
	v_max3_f32 v60, v60, v80, v82
	v_max3_f32 v60, v60, v83, v100
	v_max3_f32 v61, v61, v102, v103
	v_max3_f32 v60, v60, v101, v84
	v_max3_f32 v61, v61, v86, v87
	v_max3_f32 v60, v60, v85, v104
	v_max3_f32 v61, v61, v106, v107
	v_max3_f32 v60, v60, v105, v88
	v_max3_f32 v61, v61, v90, v91
	v_max3_f32 v60, v60, v89, v108
	v_max3_f32 v61, v61, v110, v111
	v_max3_f32 v60, v60, v109, v92
	v_max3_f32 v61, v61, v94, v95
	v_max3_f32 v60, v60, v93, v61
	v_mov_b32_e32 v61, v60
	s_nop 1
	v_permlane32_swap_b32 v60, v61
	s_nop 1
	v_add_f32_e32 v183, v203, v76
	v_max_f32_e32 v60, v60, v61
	v_cmp_lt_f32_e32 vcc, s92, v60
	s_cmp_lg_u64 vcc, 0
	s_cselect_b64 s[50:51], -1, 0
	s_cbranch_vccnz .LBB0_1392

.LBB0_1376:
	v_max_f32_e32 v92, v64, v65
	v_max3_f32 v93, v66, v67, v49
	v_max3_f32 v92, v92, v48, v50
	v_max3_f32 v92, v92, v51, v68
	v_max3_f32 v93, v93, v70, v71
	v_max3_f32 v92, v92, v69, v52
	v_max3_f32 v93, v93, v54, v55
	v_max3_f32 v92, v92, v53, v72
	v_max3_f32 v93, v93, v74, v75
	v_max3_f32 v92, v92, v73, v56
	v_max3_f32 v93, v93, v58, v59
	v_max3_f32 v92, v92, v57, v76
	v_max3_f32 v93, v93, v78, v79
	v_max3_f32 v92, v92, v77, v60
	v_max3_f32 v93, v93, v62, v63
	v_max3_f32 v92, v92, v61, v93
	v_mov_b32_e32 v93, v92
	s_nop 1
	v_permlane32_swap_b32 v92, v93
	s_nop 1
	v_add_f32_e32 v203, v183, v108
	v_max_f32_e32 v92, v92, v93
	v_cmp_lt_f32_e32 vcc, s92, v92
	s_cmp_lg_u64 vcc, 0
	s_cselect_b64 s[50:51], -1, 0
	s_cbranch_vccnz .LBB0_1395

.LBB0_1444:
	s_and_b32 s2, s33, 3
	s_mulk_i32 s2, 0x3000
	v_add_u32_e32 v84, s2, v170
	ds_read_b128 v[80:83], v84
	ds_read_b128 v[164:167], v84 offset:512
	ds_read_b128 v[180:183], v84 offset:2048
	ds_read_b128 v[184:187], v84 offset:2560
	ds_read_b128 v[196:199], v84 offset:4096
	ds_read_b128 v[200:203], v84 offset:4608
	ds_read_b128 v[204:207], v84 offset:6144
	ds_read_b128 v[208:211], v84 offset:6656
	ds_read_b128 v[218:221], v84 offset:8192
	ds_read_b128 v[222:225], v84 offset:8704
	ds_read_b128 v[226:229], v84 offset:10240
	ds_read_b128 v[230:233], v84 offset:10752
	s_and_b32 s2, s29, 0x6000
	v_add_f32_e32 v84, v64, v65
	v_add_u32_e32 v179, s2, v175
	ds_read_b64_tr_b16 v[160:161], v179 offset:49152
	ds_read_b64_tr_b16 v[162:163], v179 offset:49664
	s_waitcnt lgkmcnt(13)
	v_mfma_f32_32x32x16_bf16 v[96:111], v[80:83], v[136:139], v[32:47]
	v_add_f32_e32 v84, v66, v84
	v_add_f32_e32 v84, v67, v84
	v_add_f32_e32 v84, v68, v84
	v_cvt_pk_bf16_f32 v148, v64, v65
	v_cvt_pk_bf16_f32 v149, v66, v67
	ds_read_b64_tr_b16 v[156:157], v179 offset:53248
	ds_read_b64_tr_b16 v[158:159], v179 offset:53760
	v_add_f32_e32 v64, v69, v84
	s_waitcnt lgkmcnt(14)
	v_mfma_f32_32x32x16_bf16 v[80:95], v[164:167], v[136:139], v[32:47]
	v_add_f32_e32 v64, v70, v64
	v_add_f32_e32 v140, v71, v64
	v_cvt_pk_bf16_f32 v150, v68, v69
	v_cvt_pk_bf16_f32 v151, v70, v71
	ds_read_b64_tr_b16 v[64:65], v179 offset:50176
	ds_read_b64_tr_b16 v[66:67], v179 offset:50688
	s_waitcnt lgkmcnt(14)
	v_mfma_f32_32x32x16_bf16 v[96:111], v[180:183], v[132:135], v[96:111]
	v_add_f32_e32 v68, v72, v140
	v_add_f32_e32 v68, v73, v68
	v_add_f32_e32 v140, v74, v68
	v_cvt_pk_bf16_f32 v152, v72, v73
	v_cvt_pk_bf16_f32 v153, v74, v75
	ds_read_b64_tr_b16 v[68:69], v179 offset:54272
	ds_read_b64_tr_b16 v[70:71], v179 offset:54784
	v_mfma_f32_32x32x16_bf16 v[80:95], v[184:187], v[132:135], v[80:95]
	v_add_f32_e32 v72, v75, v140
	v_add_f32_e32 v72, v76, v72
	v_add_f32_e32 v140, v77, v72
	v_cvt_pk_bf16_f32 v154, v76, v77
	v_cvt_pk_bf16_f32 v155, v78, v79
	ds_read_b64_tr_b16 v[72:73], v179 offset:51200
	ds_read_b64_tr_b16 v[74:75], v179 offset:51712
	s_waitcnt lgkmcnt(14)
	v_mfma_f32_32x32x16_bf16 v[96:111], v[196:199], v[128:131], v[96:111]
	v_add_f32_e32 v76, v78, v140
	v_add_f32_e32 v76, v79, v76
	v_add_f32_e32 v140, v48, v76
	v_cvt_pk_bf16_f32 v144, v48, v49
	v_cvt_pk_bf16_f32 v145, v50, v51
	ds_read_b64_tr_b16 v[76:77], v179 offset:55296
	ds_read_b64_tr_b16 v[78:79], v179 offset:55808
	v_mfma_f32_32x32x16_bf16 v[80:95], v[200:203], v[128:131], v[80:95]
	v_add_f32_e32 v48, v49, v140
	v_add_f32_e32 v48, v50, v48
	v_add_f32_e32 v140, v51, v48
	v_cvt_pk_bf16_f32 v146, v52, v53
	v_cvt_pk_bf16_f32 v147, v54, v55
	ds_read_b64_tr_b16 v[48:49], v179 offset:52224
	ds_read_b64_tr_b16 v[50:51], v179 offset:52736
	v_mfma_f32_32x32x16_bf16 v[96:111], v[204:207], v[124:127], v[96:111]
	v_add_f32_e32 v52, v52, v140
	v_add_f32_e32 v52, v53, v52
	v_add_f32_e32 v52, v54, v52
	v_cvt_pk_bf16_f32 v140, v56, v57
	v_cvt_pk_bf16_f32 v141, v58, v59
	ds_read_b64_tr_b16 v[164:165], v179 offset:56320
	ds_read_b64_tr_b16 v[166:167], v179 offset:56832
	v_mfma_f32_32x32x16_bf16 v[80:95], v[208:211], v[124:127], v[80:95]
	v_add_f32_e32 v52, v55, v52
	v_add_f32_e32 v52, v56, v52
	v_add_f32_e32 v52, v57, v52
	v_cvt_pk_bf16_f32 v142, v60, v61
	v_cvt_pk_bf16_f32 v143, v62, v63
	s_waitcnt lgkmcnt(14)
	v_mfma_f32_32x32x16_bf16 v[96:111], v[218:221], v[120:123], v[96:111]
	v_add_f32_e32 v52, v58, v52
	v_add_f32_e32 v52, v59, v52
	v_add_f32_e32 v52, v60, v52
	v_mfma_f32_32x32x16_bf16 v[80:95], v[222:225], v[120:123], v[80:95]
	v_add_f32_e32 v52, v61, v52
	v_add_f32_e32 v52, v62, v52
	v_add_f32_e32 v52, v63, v52
	v_mfma_f32_32x32x16_bf16 v[96:111], v[226:229], v[116:119], v[96:111]
	v_mfma_f32_32x32x16_bf16 v[80:95], v[230:233], v[116:119], v[80:95]
	s_nop 10
	v_max_f32_e32 v53, v96, v97
	v_max3_f32 v54, v98, v99, v81
	v_max3_f32 v53, v53, v80, v82
	v_max3_f32 v53, v53, v83, v100
	v_max3_f32 v54, v54, v102, v103
	v_max3_f32 v53, v53, v101, v84
	v_max3_f32 v54, v54, v86, v87
	v_max3_f32 v53, v53, v85, v104
	v_max3_f32 v54, v54, v106, v107
	v_max3_f32 v53, v53, v105, v88
	v_max3_f32 v54, v54, v90, v91
	v_max3_f32 v53, v53, v89, v108
	v_max3_f32 v54, v54, v110, v111
	v_max3_f32 v53, v53, v109, v92
	v_max3_f32 v54, v54, v94, v95
	v_add_f32_e32 v178, v178, v52
	v_max3_f32 v52, v53, v93, v54
	v_mov_b32_e32 v53, v52
	s_nop 1
	v_permlane32_swap_b32 v52, v53
	s_nop 1
	s_nop 0
	v_max_f32_e32 v52, v52, v53
	v_cmp_lt_f32_e32 vcc, s92, v52
	s_cmp_lg_u64 vcc, 0
	s_cselect_b64 s[48:49], -1, 0
	s_cbranch_vccnz .LBB0_1471

.LBB0_1458:
	s_add_i32 s2, s28, -2
	s_and_b32 s2, s2, 3
	s_mulk_i32 s2, 0x3000
	v_add_u32_e32 v52, s2, v170
	ds_read_b128 v[48:51], v52
	ds_read_b128 v[164:167], v52 offset:512
	ds_read_b128 v[180:183], v52 offset:2048
	ds_read_b128 v[184:187], v52 offset:2560
	ds_read_b128 v[196:199], v52 offset:4096
	ds_read_b128 v[200:203], v52 offset:4608
	ds_read_b128 v[204:207], v52 offset:6144
	ds_read_b128 v[208:211], v52 offset:6656
	ds_read_b128 v[218:221], v52 offset:8192
	ds_read_b128 v[222:225], v52 offset:8704
	ds_read_b128 v[226:229], v52 offset:10240
	ds_read_b128 v[230:233], v52 offset:10752
	s_add_i32 s2, s29, 0xffffa000
	s_and_b32 s2, s2, 0x6000
	v_add_f32_e32 v52, v96, v97
	v_add_u32_e32 v179, s2, v175
	ds_read_b64_tr_b16 v[160:161], v179 offset:49152
	ds_read_b64_tr_b16 v[162:163], v179 offset:49664
	s_waitcnt lgkmcnt(13)
	v_mfma_f32_32x32x16_bf16 v[64:79], v[48:51], v[136:139], v[32:47]
	v_add_f32_e32 v52, v98, v52
	v_add_f32_e32 v52, v99, v52
	v_add_f32_e32 v52, v100, v52
	v_cvt_pk_bf16_f32 v148, v96, v97
	v_cvt_pk_bf16_f32 v149, v98, v99
	ds_read_b64_tr_b16 v[156:157], v179 offset:53248
	ds_read_b64_tr_b16 v[158:159], v179 offset:53760
	v_add_f32_e32 v48, v101, v52
	v_add_f32_e32 v48, v102, v48
	v_add_f32_e32 v140, v103, v48
	s_waitcnt lgkmcnt(14)
	v_mfma_f32_32x32x16_bf16 v[48:63], v[164:167], v[136:139], v[32:47]
	v_cvt_pk_bf16_f32 v150, v100, v101
	v_cvt_pk_bf16_f32 v151, v102, v103
	ds_read_b64_tr_b16 v[96:97], v179 offset:50176
	ds_read_b64_tr_b16 v[98:99], v179 offset:50688
	s_waitcnt lgkmcnt(14)
	v_mfma_f32_32x32x16_bf16 v[64:79], v[180:183], v[132:135], v[64:79]
	v_add_f32_e32 v100, v104, v140
	v_add_f32_e32 v100, v105, v100
	v_add_f32_e32 v140, v106, v100
	v_cvt_pk_bf16_f32 v152, v104, v105
	v_cvt_pk_bf16_f32 v153, v106, v107
	ds_read_b64_tr_b16 v[100:101], v179 offset:54272
	ds_read_b64_tr_b16 v[102:103], v179 offset:54784
	v_mfma_f32_32x32x16_bf16 v[48:63], v[184:187], v[132:135], v[48:63]
	v_add_f32_e32 v104, v107, v140
	v_add_f32_e32 v104, v108, v104
	v_add_f32_e32 v140, v109, v104
	v_cvt_pk_bf16_f32 v154, v108, v109
	v_cvt_pk_bf16_f32 v155, v110, v111
	ds_read_b64_tr_b16 v[104:105], v179 offset:51200
	ds_read_b64_tr_b16 v[106:107], v179 offset:51712
	s_waitcnt lgkmcnt(14)
	v_mfma_f32_32x32x16_bf16 v[64:79], v[196:199], v[128:131], v[64:79]
	v_add_f32_e32 v108, v110, v140
	v_add_f32_e32 v108, v111, v108
	v_add_f32_e32 v140, v80, v108
	v_cvt_pk_bf16_f32 v144, v80, v81
	v_cvt_pk_bf16_f32 v145, v82, v83
	ds_read_b64_tr_b16 v[108:109], v179 offset:55296
	ds_read_b64_tr_b16 v[110:111], v179 offset:55808
	v_mfma_f32_32x32x16_bf16 v[48:63], v[200:203], v[128:131], v[48:63]
	v_add_f32_e32 v80, v81, v140
	v_add_f32_e32 v80, v82, v80
	v_add_f32_e32 v140, v83, v80
	v_cvt_pk_bf16_f32 v146, v84, v85
	v_cvt_pk_bf16_f32 v147, v86, v87
	ds_read_b64_tr_b16 v[80:81], v179 offset:52224
	ds_read_b64_tr_b16 v[82:83], v179 offset:52736
	v_mfma_f32_32x32x16_bf16 v[64:79], v[204:207], v[124:127], v[64:79]
	v_add_f32_e32 v84, v84, v140
	v_add_f32_e32 v84, v85, v84
	v_add_f32_e32 v84, v86, v84
	v_cvt_pk_bf16_f32 v140, v88, v89
	v_cvt_pk_bf16_f32 v141, v90, v91
	ds_read_b64_tr_b16 v[164:165], v179 offset:56320
	ds_read_b64_tr_b16 v[166:167], v179 offset:56832
	v_mfma_f32_32x32x16_bf16 v[48:63], v[208:211], v[124:127], v[48:63]
	v_add_f32_e32 v84, v87, v84
	v_add_f32_e32 v84, v88, v84
	v_add_f32_e32 v84, v89, v84
	v_cvt_pk_bf16_f32 v142, v92, v93
	v_cvt_pk_bf16_f32 v143, v94, v95
	s_waitcnt lgkmcnt(14)
	v_mfma_f32_32x32x16_bf16 v[64:79], v[218:221], v[120:123], v[64:79]
	v_add_f32_e32 v84, v90, v84
	v_add_f32_e32 v84, v91, v84
	v_add_f32_e32 v84, v92, v84
	v_mfma_f32_32x32x16_bf16 v[48:63], v[222:225], v[120:123], v[48:63]
	v_add_f32_e32 v84, v93, v84
	v_add_f32_e32 v84, v94, v84
	v_add_f32_e32 v84, v95, v84
	v_mfma_f32_32x32x16_bf16 v[64:79], v[226:229], v[116:119], v[64:79]
	v_mfma_f32_32x32x16_bf16 v[48:63], v[230:233], v[116:119], v[48:63]
	s_nop 10
	v_max_f32_e32 v85, v64, v65
	v_max3_f32 v86, v66, v67, v49
	v_max3_f32 v85, v85, v48, v50
	v_max3_f32 v85, v85, v51, v68
	v_max3_f32 v86, v86, v70, v71
	v_max3_f32 v85, v85, v69, v52
	v_max3_f32 v86, v86, v54, v55
	v_max3_f32 v85, v85, v53, v72
	v_max3_f32 v86, v86, v74, v75
	v_max3_f32 v85, v85, v73, v56
	v_max3_f32 v86, v86, v58, v59
	v_max3_f32 v85, v85, v57, v76
	v_max3_f32 v86, v86, v78, v79
	v_max3_f32 v85, v85, v77, v60
	v_max3_f32 v86, v86, v62, v63
	v_add_f32_e32 v178, v178, v84
	v_max3_f32 v84, v85, v61, v86
	v_mov_b32_e32 v85, v84
	s_nop 1
	v_permlane32_swap_b32 v85, v84
	s_nop 1
	s_nop 0
	v_max_f32_e32 v84, v85, v84
	v_cmp_lt_f32_e32 vcc, s92, v84
	s_cmp_lg_u64 vcc, 0
	s_cselect_b64 s[50:51], -1, 0
	s_cbranch_vccnz .LBB0_1474
